# Attention unit loops shifted by 4 bytes so that the steady-state and band loop heads sit on 8-byte boundaries (s_nop pad at phase entry, compensated at exit)
# speedup vs baseline: 1.0698x; 1.0035x over previous
.LBB0_229:
	v_lshlrev_b32_e32 v225, 2, v206
	v_add_u32_e32 v225, 0x1b000, v225
	ds_write_b32 v225, v254
	s_nop 0
	s_mov_b32 s26, 0xffff0000
	s_mov_b32 s9, 0
	v_mov_b32_e32 v1, 0
	s_mov_b64 s[10:11], 0x12000000
	s_mov_b64 s[12:13], 0x14000000
	s_mov_b64 s[14:15], 0x12010000
	s_mov_b64 s[16:17], 0x10000000
	s_brev_b32 s51, 8
	s_mov_b64 s[18:19], 0x12020000
	s_mov_b64 s[20:21], 0x30000
	s_mov_b64 s[22:23], 0x10000
	s_mov_b64 s[24:25], 0x50000
	s_mov_b32 s27, -1
	s_mov_b32 s52, 0x41000000
	s_mov_b64 s[28:29], 0x20000
	s_mov_b64 s[30:31], 0x40000
	s_mov_b64 s[34:35], 0x1c000000
	v_mov_b32_e32 v207, 0xff800000
	s_branch .LBB0_231

.Lattn_rest_0:
	s_nop 0
	v_lshlrev_b32_e32 v225, 2, v206
	v_add_u32_e32 v225, 0x1b000, v225
	ds_read_b32 v254, v225
	s_waitcnt lgkmcnt(0)

.LBB0_1709:
	v_lshlrev_b32_e32 v225, 2, v206
	v_add_u32_e32 v225, 0x1b000, v225
	ds_write_b32 v225, v254
	s_nop 0
	s_mov_b32 s26, 0xffff0000
	s_mov_b32 s9, 0
	v_mov_b32_e32 v1, 0
	s_mov_b64 s[10:11], 0x12000000
	s_mov_b64 s[12:13], 0x14000000
	s_mov_b64 s[14:15], 0x12010000
	s_mov_b64 s[16:17], 0x10000000
	s_brev_b32 s51, 8
	s_mov_b64 s[18:19], 0x12020000
	s_mov_b64 s[20:21], 0x30000
	s_mov_b64 s[22:23], 0x10000
	s_mov_b64 s[24:25], 0x50000
	s_mov_b32 s27, -1
	s_mov_b32 s52, 0x41000000
	s_mov_b64 s[28:29], 0x20000
	s_mov_b64 s[30:31], 0x40000
	s_mov_b64 s[34:35], 0x1c000000
	v_mov_b32_e32 v208, 0xff800000
	s_branch .LBB0_1711
